# FFN1 conv-gate GEMM epilogue (phase 9): the 120 packed f32 ops as per-element ops
# speedup vs baseline: 1.0025x; 1.0025x over previous
; #define GAS __attribute__((address_space(1)))
; __device__ __forceinline__ unsigned pk2(float lo, float hi) { const f32x2cv v = {lo, hi}; return __builtin_bit_cast(unsigned, __builtin_convertvector(v, bf16x2cv)); }
; __device__ __forceinline__ float siluf_(float x) { return x * __builtin_amdgcn_rcpf(1.0f + __builtin_amdgcn_exp2f(-1.4426950408889634f * x)); }
;     __device__ __forceinline__ void operator()(const pg8::f32x4 (&acc)[2][2][4][2], const pg8::Unit& u, int wr, int wc, int fr, int fq) const {
;         const int hc0 = 128 * u.pn + 32 * wc + 8 * fq;
;         v4u wq[4];
; #pragma unroll
;         for (int i = 0; i < 4; ++i) wq[i] = *(const GAS v4u*)(cwt + (size_t)(hc0 + 2 * i) * 4);
; #pragma unroll
;         for (int ai = 0; ai < 2; ++ai) {
;             const int rowbase = u.pm * 256 + 128 * ai + 64 * wr, g64 = rowbase >> 6;
; #pragma unroll
;             for (int n = 0; n < 2; ++n) {
;                 const int hc = hc0 + 4 * n;
;                 float out[4][4];
; #pragma unroll
;                 for (int e = 0; e < 4; ++e) { const int c = 4 * n + e; const unsigned pw0 = (c & 1) ? wq[c >> 1].z : wq[c >> 1].x, pw1 = (c & 1) ? wq[c >> 1].w : wq[c >> 1].y;
;                     const float w0 = bflo(pw0), w1 = bfhi(pw0), w2 = bflo(pw1), b0 = bfhi(pw1);
;                     float a[4], up[4], dn[4];
; #pragma unroll
;                     for (int m = 0; m < 4; ++m) { a[m] = acc[ai][0][m][n][e];
;                         up[m] = __builtin_bit_cast(float, __builtin_amdgcn_mov_dpp(__builtin_bit_cast(int, a[m]), 0x121, 0xf, 0xf, false));
;                         dn[m] = __builtin_bit_cast(float, __builtin_amdgcn_mov_dpp(__builtin_bit_cast(int, a[m]), 0x12f, 0xf, 0xf, false)); }
; #pragma unroll
;                     for (int m = 0; m < 4; ++m) { const float prev = fr > 0 ? up[m] : (m > 0 ? up[m > 0 ? m - 1 : 0] : 0.f), next = fr < 15 ? dn[m] : (m < 3 ? dn[m < 3 ? m + 1 : 3] : 0.f);
;                         const float cv = b0 + w0 * prev + w1 * a[m] + w2 * next; out[m][e] = siluf_(cv) * acc[ai][1][m][n][e]; } }
; #pragma unroll
;                 for (int m = 0; m < 4; ++m) { const int r64 = 16 * m + fr, row = rowbase + r64;
;                     if (r64 != 0 && r64 != 63) { v2u w; w.x = pk2(out[m][0], out[m][1]); w.y = pk2(out[m][2], out[m][3]); *(GAS v2u*)(hg + (size_t)row * FFH + hc) = w; }
.LBB0_1531:
	v_lshl_or_b32 v154, s40, 7, v181
	v_ashrrev_i32_e32 v155, 31, v154
	v_lshl_add_u64 v[134:135], v[154:155], 3, s[22:23]
	global_load_dwordx4 v[156:159], v[134:135], off
	global_load_dwordx4 v[214:217], v[134:135], off offset:16
	global_load_dwordx4 v[130:133], v[134:135], off offset:48
	s_nop 0
	global_load_dwordx4 v[134:137], v[134:135], off offset:32
	s_lshl_b32 s29, s38, 8
	s_add_i32 s29, s29, s58
	v_mov_b32_dpp v174, v126 row_ror:1 row_mask:0xf bank_mask:0xf
	v_mov_b32_dpp v186, v126 row_ror:15 row_mask:0xf bank_mask:0xf
	v_mov_b32_dpp v206, v118 row_ror:1 row_mask:0xf bank_mask:0xf
	v_mov_b32_dpp v209, v118 row_ror:15 row_mask:0xf bank_mask:0xf
	v_mov_b32_dpp v188, v114 row_ror:1 row_mask:0xf bank_mask:0xf
	v_mov_b32_dpp v207, v114 row_ror:15 row_mask:0xf bank_mask:0xf
	v_mov_b32_dpp v189, v102 row_ror:1 row_mask:0xf bank_mask:0xf
	v_mov_b32_dpp v187, v102 row_ror:15 row_mask:0xf bank_mask:0xf
	v_mov_b32_dpp v175, v127 row_ror:1 row_mask:0xf bank_mask:0xf
	v_mov_b32_dpp v211, v127 row_ror:15 row_mask:0xf bank_mask:0xf
	v_mov_b32_dpp v203, v119 row_ror:1 row_mask:0xf bank_mask:0xf
	v_mov_b32_dpp v210, v119 row_ror:15 row_mask:0xf bank_mask:0xf
	v_mov_b32_dpp v191, v115 row_ror:1 row_mask:0xf bank_mask:0xf
	v_mov_b32_dpp v205, v115 row_ror:15 row_mask:0xf bank_mask:0xf
	v_mov_b32_dpp v193, v103 row_ror:1 row_mask:0xf bank_mask:0xf
	v_mov_b32_dpp v190, v103 row_ror:15 row_mask:0xf bank_mask:0xf
	v_mov_b32_dpp v172, v128 row_ror:1 row_mask:0xf bank_mask:0xf
	v_mov_b32_dpp v212, v128 row_ror:15 row_mask:0xf bank_mask:0xf
	v_mov_b32_dpp v201, v120 row_ror:1 row_mask:0xf bank_mask:0xf
	v_mov_b32_dpp v204, v120 row_ror:15 row_mask:0xf bank_mask:0xf
	v_mov_b32_dpp v194, v116 row_ror:1 row_mask:0xf bank_mask:0xf
	v_mov_b32_dpp v202, v116 row_ror:15 row_mask:0xf bank_mask:0xf
	v_mov_b32_dpp v195, v104 row_ror:1 row_mask:0xf bank_mask:0xf
	v_mov_b32_dpp v192, v104 row_ror:15 row_mask:0xf bank_mask:0xf
	v_mov_b32_dpp v173, v129 row_ror:1 row_mask:0xf bank_mask:0xf
	v_mov_b32_dpp v213, v129 row_ror:15 row_mask:0xf bank_mask:0xf
	v_mov_b32_dpp v199, v121 row_ror:1 row_mask:0xf bank_mask:0xf
	v_mov_b32_dpp v208, v121 row_ror:15 row_mask:0xf bank_mask:0xf
	v_mov_b32_dpp v197, v117 row_ror:1 row_mask:0xf bank_mask:0xf
	v_mov_b32_dpp v200, v117 row_ror:15 row_mask:0xf bank_mask:0xf
	v_mov_b32_dpp v198, v105 row_ror:1 row_mask:0xf bank_mask:0xf
	v_mov_b32_dpp v196, v105 row_ror:15 row_mask:0xf bank_mask:0xf
	v_or_b32_e32 v185, s29, v1
	s_waitcnt vmcnt(0)
	v_lshlrev_b32_e32 v165, 16, v158
	v_lshlrev_b32_e32 v164, 16, v156
	v_and_b32_e32 v167, 0xffff0000, v159
	v_and_b32_e32 v166, 0xffff0000, v157
	v_and_b32_e32 v169, 0xffff0000, v158
	v_and_b32_e32 v168, 0xffff0000, v156
	v_lshlrev_b32_e32 v171, 16, v159
	v_lshlrev_b32_e32 v170, 16, v157
	v_lshlrev_b32_e32 v157, 16, v216
	v_lshlrev_b32_e32 v156, 16, v214
	v_and_b32_e32 v159, 0xffff0000, v217
	v_and_b32_e32 v158, 0xffff0000, v215
	v_and_b32_e32 v161, 0xffff0000, v216
	v_and_b32_e32 v160, 0xffff0000, v214
	v_lshlrev_b32_e32 v163, 16, v217
	v_lshlrev_b32_e32 v162, 16, v215
	s_and_saveexec_b64 s[38:39], s[4:5]
	s_cbranch_execz .LBB0_1533
	v_fma_f32 v214, v156, v172, v158
	v_fma_f32 v215, v157, v173, v159
	v_cndmask_b32_e64 v213, v213, v208, s[6:7]
	v_fma_f32 v214, v128, v160, v214
	v_fma_f32 v215, v129, v161, v215
	v_cndmask_b32_e64 v212, v212, v204, s[6:7]
	v_fma_f32 v212, v212, v162, v214
	v_fma_f32 v213, v213, v163, v215
	v_cndmask_b32_e64 v219, v211, v210, s[6:7]
	v_mul_f32_e32 v214, 0xbfb8aa3b, v213
	v_exp_f32_e32 v214, v214
	v_mul_f32_e32 v215, 0xbfb8aa3b, v212
	v_exp_f32_e32 v216, v215
	v_cndmask_b32_e64 v218, v186, v209, s[6:7]
	v_add_f32_e32 v214, 1.0, v214
	v_rcp_f32_e32 v215, v214
	v_add_f32_e32 v214, 1.0, v216
	v_fma_f32 v216, v164, v174, v166
	v_fma_f32 v217, v165, v175, v167
	v_rcp_f32_e32 v214, v214
	v_fma_f32 v216, v126, v168, v216
	v_fma_f32 v217, v127, v169, v217
	v_mul_f32_e32 v212, v212, v214
	v_mul_f32_e32 v213, v213, v215
	v_fma_f32 v216, v218, v170, v216
	v_fma_f32 v217, v219, v171, v217
	v_mul_f32_e32 v212, v124, v212
	v_mul_f32_e32 v213, v125, v213
	v_mul_f32_e32 v186, 0xbfb8aa3b, v217
	v_exp_f32_e32 v186, v186
	v_mul_f32_e32 v211, 0xbfb8aa3b, v216
	v_exp_f32_e32 v211, v211
	v_add_f32_e32 v186, 1.0, v186
	v_rcp_f32_e32 v219, v186
	v_add_f32_e32 v186, 1.0, v211
	v_rcp_f32_e32 v218, v186
	s_nop 0
	v_mul_f32_e32 v214, v216, v218
	v_mul_f32_e32 v215, v217, v219
	s_nop 0
	v_mul_f32_e32 v214, v122, v214
	v_mul_f32_e32 v215, v123, v215
	s_nop 0
	v_cvt_pk_bf16_f32 v214, v214, v215
	v_cvt_pk_bf16_f32 v215, v212, v213
	v_mov_b64_e32 v[212:213], s[18:19]
	v_mad_i64_i32 v[212:213], s[42:43], v185, s65, v[212:213]
	v_lshl_add_u64 v[212:213], v[154:155], 1, v[212:213]
	global_store_dwordx2 v[212:213], v[214:215], off

; #define GAS __attribute__((address_space(1)))
; __device__ __forceinline__ unsigned pk2(float lo, float hi) { const f32x2cv v = {lo, hi}; return __builtin_bit_cast(unsigned, __builtin_convertvector(v, bf16x2cv)); }
; __device__ __forceinline__ float siluf_(float x) { return x * __builtin_amdgcn_rcpf(1.0f + __builtin_amdgcn_exp2f(-1.4426950408889634f * x)); }
;     __device__ __forceinline__ void operator()(const pg8::f32x4 (&acc)[2][2][4][2], const pg8::Unit& u, int wr, int wc, int fr, int fq) const {
;     ...
;                 for (int e = 0; e < 4; ++e) { const int c = 4 * n + e; const unsigned pw0 = (c & 1) ? wq[c >> 1].z : wq[c >> 1].x, pw1 = (c & 1) ? wq[c >> 1].w : wq[c >> 1].y;
;                     const float w0 = bflo(pw0), w1 = bfhi(pw0), w2 = bflo(pw1), b0 = bfhi(pw1);
;                     float a[4], up[4], dn[4];
; #pragma unroll
;                     for (int m = 0; m < 4; ++m) { a[m] = acc[ai][0][m][n][e];
;                         up[m] = __builtin_bit_cast(float, __builtin_amdgcn_mov_dpp(__builtin_bit_cast(int, a[m]), 0x121, 0xf, 0xf, false));
;                         dn[m] = __builtin_bit_cast(float, __builtin_amdgcn_mov_dpp(__builtin_bit_cast(int, a[m]), 0x12f, 0xf, 0xf, false)); }
; #pragma unroll
;                     for (int m = 0; m < 4; ++m) { const float prev = fr > 0 ? up[m] : (m > 0 ? up[m > 0 ? m - 1 : 0] : 0.f), next = fr < 15 ? dn[m] : (m < 3 ? dn[m < 3 ? m + 1 : 3] : 0.f);
;                         const float cv = b0 + w0 * prev + w1 * a[m] + w2 * next; out[m][e] = siluf_(cv) * acc[ai][1][m][n][e]; } }
; #pragma unroll
;                 for (int m = 0; m < 4; ++m) { const int r64 = 16 * m + fr, row = rowbase + r64;
;                     if (r64 != 0 && r64 != 63) { v2u w; w.x = pk2(out[m][0], out[m][1]); w.y = pk2(out[m][2], out[m][3]); *(GAS v2u*)(hg + (size_t)row * FFH + hc) = w; }
.LBB0_1536:
	s_or_b64 exec, exec, s[38:39]
	v_cndmask_b32_e64 v123, v203, v175, s[2:3]
	v_cndmask_b32_e64 v122, v206, v174, s[2:3]
	v_fma_f32 v122, v122, v164, v166
	v_fma_f32 v123, v123, v165, v167
	v_cndmask_b32_e64 v125, v210, v205, s[6:7]
	v_cndmask_b32_e64 v124, v209, v207, s[6:7]
	v_fma_f32 v118, v118, v168, v122
	v_fma_f32 v119, v119, v169, v123
	v_cndmask_b32_e64 v126, v205, v190, s[6:7]
	v_fma_f32 v118, v124, v170, v118
	v_fma_f32 v119, v125, v171, v119
	v_cndmask_b32_e64 v124, v188, v206, s[2:3]
	v_mul_f32_e32 v122, 0xbfb8aa3b, v118
	v_mul_f32_e32 v123, 0xbfb8aa3b, v119
	v_fma_f32 v124, v164, v124, v166
	v_exp_f32_e32 v122, v122
	v_exp_f32_e32 v123, v123
	v_cndmask_b32_e64 v125, v207, v187, s[6:7]
	v_fmac_f32_e32 v124, v114, v168
	v_fmac_f32_e32 v124, v170, v125
	v_mul_f32_e32 v114, 0xbfb8aa3b, v124
	v_exp_f32_e32 v125, v114
	v_cndmask_b32_e64 v114, v191, v203, s[2:3]
	v_add_f32_e32 v122, 1.0, v122
	v_add_f32_e32 v123, 1.0, v123
	v_fma_f32 v127, v165, v114, v167
	v_rcp_f32_e32 v122, v122
	v_rcp_f32_e32 v123, v123
	v_fmac_f32_e32 v127, v115, v169
	v_fmac_f32_e32 v127, v171, v126
	v_mul_f32_e32 v114, 0xbfb8aa3b, v127
	v_exp_f32_e32 v126, v114
	v_mul_f32_e32 v114, v118, v122
	v_mul_f32_e32 v115, v119, v123
	v_add_f32_e32 v118, 1.0, v125
	v_rcp_f32_e32 v118, v118
	v_add_f32_e32 v119, 1.0, v126
	v_rcp_f32_e32 v119, v119
	v_mul_f32_e32 v110, v110, v114
	v_mul_f32_e32 v111, v111, v115
	v_mul_f32_e32 v114, v124, v118
	v_mul_f32_e32 v122, v106, v114
	v_cndmask_b32_e64 v115, v199, v173, s[2:3]
	v_cndmask_b32_e64 v114, v201, v172, s[2:3]
	v_fma_f32 v114, v114, v156, v158
	v_fma_f32 v115, v115, v157, v159
	v_mul_f32_e32 v106, v127, v119
	v_cndmask_b32_e64 v119, v208, v200, s[6:7]
	v_cndmask_b32_e64 v118, v204, v202, s[6:7]
	v_fma_f32 v114, v120, v160, v114
	v_fma_f32 v115, v121, v161, v115
	v_mul_f32_e32 v120, v107, v106
	v_fma_f32 v114, v118, v162, v114
	v_fma_f32 v115, v119, v163, v115
	v_cndmask_b32_e64 v121, v200, v196, s[6:7]
	v_mul_f32_e32 v118, 0xbfb8aa3b, v114
	v_exp_f32_e32 v118, v118
	v_mul_f32_e32 v119, 0xbfb8aa3b, v115
	v_exp_f32_e32 v119, v119
	v_or_b32_e32 v124, s29, v179
	v_add_f32_e32 v106, 1.0, v118
	v_cndmask_b32_e64 v118, v194, v201, s[2:3]
	v_fma_f32 v118, v156, v118, v158
	v_add_f32_e32 v107, 1.0, v119
	v_cndmask_b32_e64 v119, v202, v192, s[6:7]
	v_fmac_f32_e32 v118, v116, v160
	v_fmac_f32_e32 v118, v162, v119
	v_cndmask_b32_e64 v119, v197, v199, s[2:3]
	v_fma_f32 v119, v157, v119, v159
	v_fmac_f32_e32 v119, v117, v161
	v_mul_f32_e32 v116, 0xbfb8aa3b, v118
	v_fmac_f32_e32 v119, v163, v121
	v_rcp_f32_e32 v106, v106
	v_rcp_f32_e32 v107, v107
	v_exp_f32_e32 v116, v116
	v_mul_f32_e32 v117, 0xbfb8aa3b, v119
	v_exp_f32_e32 v117, v117
	v_mul_f32_e32 v106, v114, v106
	v_mul_f32_e32 v107, v115, v107
	v_add_f32_e32 v114, 1.0, v116
	v_rcp_f32_e32 v114, v114
	v_add_f32_e32 v115, 1.0, v117
	v_rcp_f32_e32 v115, v115
	v_mul_f32_e32 v106, v112, v106
	v_mul_f32_e32 v107, v113, v107
	v_mul_f32_e32 v112, v118, v114
	v_mul_f32_e32 v112, v108, v112
	v_mul_f32_e32 v108, v119, v115
	v_mul_f32_e32 v113, v109, v108
	v_or_b32_e32 v114, s29, v177
	v_cvt_pk_bf16_f32 v109, v106, v107
	v_mov_b64_e32 v[106:107], s[18:19]
	v_cvt_pk_bf16_f32 v108, v110, v111
	v_mad_i64_i32 v[110:111], s[38:39], v114, s65, v[106:107]
	v_lshlrev_b64 v[114:115], 1, v[154:155]
	v_lshl_add_u64 v[116:117], v[110:111], 0, v[114:115]
	v_or_b32_e32 v110, s29, v178
	v_mad_i64_i32 v[106:107], s[38:39], v110, s65, v[106:107]
	global_store_dwordx2 v[116:117], v[108:109], off
	v_cvt_pk_bf16_f32 v108, v122, v120
	v_cvt_pk_bf16_f32 v109, v112, v113
	v_lshl_add_u64 v[118:119], v[106:107], 0, v[114:115]
	global_store_dwordx2 v[118:119], v[108:109], off
	s_and_saveexec_b64 s[38:39], s[8:9]
	s_cbranch_execz .LBB0_1538
	v_cndmask_b32_e64 v106, v189, v188, s[2:3]
	v_cndmask_b32_e64 v107, v193, v191, s[2:3]
	v_cndmask_b32_e64 v110, v195, v194, s[2:3]
	v_cndmask_b32_e64 v111, v198, v197, s[2:3]
	v_fma_f32 v106, v106, v164, v166
	v_fma_f32 v107, v107, v165, v167
	v_fma_f32 v110, v110, v156, v158
	v_fma_f32 v111, v111, v157, v159
	v_cndmask_b32_e64 v108, v187, 0, s[6:7]
	v_cndmask_b32_e64 v109, v190, 0, s[6:7]
	v_fma_f32 v106, v102, v168, v106
	v_fma_f32 v107, v103, v169, v107
	v_cndmask_b32_e64 v112, v192, 0, s[6:7]
	v_cndmask_b32_e64 v113, v196, 0, s[6:7]
	v_fma_f32 v110, v104, v160, v110
	v_fma_f32 v111, v105, v161, v111
	v_fma_f32 v106, v108, v170, v106
	v_fma_f32 v107, v109, v171, v107
	v_fma_f32 v110, v112, v162, v110
	v_fma_f32 v111, v113, v163, v111
	v_mul_f32_e32 v108, 0xbfb8aa3b, v106
	v_mul_f32_e32 v109, 0xbfb8aa3b, v107
	v_mul_f32_e32 v112, 0xbfb8aa3b, v110
	v_mul_f32_e32 v113, 0xbfb8aa3b, v111
	v_exp_f32_e32 v108, v108
	v_exp_f32_e32 v109, v109
	v_exp_f32_e32 v112, v112
	v_exp_f32_e32 v113, v113
	v_add_f32_e32 v108, 1.0, v108
	v_add_f32_e32 v109, 1.0, v109
	v_add_f32_e32 v112, 1.0, v112
	v_add_f32_e32 v113, 1.0, v113
	v_rcp_f32_e32 v108, v108
	v_rcp_f32_e32 v109, v109
	v_rcp_f32_e32 v112, v112
	v_rcp_f32_e32 v113, v113
	v_mul_f32_e32 v106, v106, v108
	v_mul_f32_e32 v107, v107, v109
	s_nop 0
	v_mul_f32_e32 v106, v98, v106
	v_mul_f32_e32 v107, v99, v107
	v_mul_f32_e32 v108, v110, v112
	v_mul_f32_e32 v109, v111, v113
	v_cvt_pk_bf16_f32 v106, v106, v107
	v_mul_f32_e32 v108, v100, v108
	v_mul_f32_e32 v109, v101, v109
	s_nop 0
	v_cvt_pk_bf16_f32 v107, v108, v109
	v_mov_b64_e32 v[108:109], s[18:19]
	v_mad_i64_i32 v[108:109], s[42:43], v124, s65, v[108:109]
	v_lshl_add_u64 v[108:109], v[154:155], 1, v[108:109]
	global_store_dwordx2 v[108:109], v[106:107], off

; #define GAS __attribute__((address_space(1)))
; __device__ __forceinline__ unsigned pk2(float lo, float hi) { const f32x2cv v = {lo, hi}; return __builtin_bit_cast(unsigned, __builtin_convertvector(v, bf16x2cv)); }
; __device__ __forceinline__ float siluf_(float x) { return x * __builtin_amdgcn_rcpf(1.0f + __builtin_amdgcn_exp2f(-1.4426950408889634f * x)); }
;     __device__ __forceinline__ void operator()(const pg8::f32x4 (&acc)[2][2][4][2], const pg8::Unit& u, int wr, int wc, int fr, int fq) const {
;     ...
;         for (int ai = 0; ai < 2; ++ai) {
;             const int rowbase = u.pm * 256 + 128 * ai + 64 * wr, g64 = rowbase >> 6;
; #pragma unroll
;             for (int n = 0; n < 2; ++n) {
;                 const int hc = hc0 + 4 * n;
;                 float out[4][4];
; #pragma unroll
;                 for (int e = 0; e < 4; ++e) { const int c = 4 * n + e; const unsigned pw0 = (c & 1) ? wq[c >> 1].z : wq[c >> 1].x, pw1 = (c & 1) ? wq[c >> 1].w : wq[c >> 1].y;
;                     const float w0 = bflo(pw0), w1 = bfhi(pw0), w2 = bflo(pw1), b0 = bfhi(pw1);
;                     float a[4], up[4], dn[4];
; #pragma unroll
;                     for (int m = 0; m < 4; ++m) { a[m] = acc[ai][0][m][n][e];
;                         up[m] = __builtin_bit_cast(float, __builtin_amdgcn_mov_dpp(__builtin_bit_cast(int, a[m]), 0x121, 0xf, 0xf, false));
;                         dn[m] = __builtin_bit_cast(float, __builtin_amdgcn_mov_dpp(__builtin_bit_cast(int, a[m]), 0x12f, 0xf, 0xf, false)); }
; #pragma unroll
;                     for (int m = 0; m < 4; ++m) { const float prev = fr > 0 ? up[m] : (m > 0 ? up[m > 0 ? m - 1 : 0] : 0.f), next = fr < 15 ? dn[m] : (m < 3 ? dn[m < 3 ? m + 1 : 3] : 0.f);
;                         const float cv = b0 + w0 * prev + w1 * a[m] + w2 * next; out[m][e] = siluf_(cv) * acc[ai][1][m][n][e]; } }
; #pragma unroll
;                 for (int m = 0; m < 4; ++m) { const int r64 = 16 * m + fr, row = rowbase + r64;
;                     if (r64 != 0 && r64 != 63) { v2u w; w.x = pk2(out[m][0], out[m][1]); w.y = pk2(out[m][2], out[m][3]); *(GAS v2u*)(hg + (size_t)row * FFH + hc) = w; }
.LBB0_1541:
	s_or_b64 exec, exec, s[38:39]
	v_lshlrev_b32_e32 v99, 16, v136
	v_lshlrev_b32_e32 v98, 16, v134
	v_and_b32_e32 v101, 0xffff0000, v136
	v_and_b32_e32 v100, 0xffff0000, v134
	v_lshlrev_b32_e32 v103, 16, v137
	v_lshlrev_b32_e32 v102, 16, v135
	v_and_b32_e32 v105, 0xffff0000, v137
	v_and_b32_e32 v104, 0xffff0000, v135
	v_mov_b32_dpp v122, v94 row_ror:1 row_mask:0xf bank_mask:0xf
	v_mov_b32_dpp v195, v94 row_ror:15 row_mask:0xf bank_mask:0xf
	v_mov_b32_dpp v190, v86 row_ror:1 row_mask:0xf bank_mask:0xf
	v_mov_b32_dpp v193, v86 row_ror:15 row_mask:0xf bank_mask:0xf
	v_mov_b32_dpp v127, v82 row_ror:1 row_mask:0xf bank_mask:0xf
	v_mov_b32_dpp v191, v82 row_ror:15 row_mask:0xf bank_mask:0xf
	v_mov_b32_dpp v128, v70 row_ror:1 row_mask:0xf bank_mask:0xf
	v_mov_b32_dpp v126, v70 row_ror:15 row_mask:0xf bank_mask:0xf
	v_mov_b32_dpp v123, v95 row_ror:1 row_mask:0xf bank_mask:0xf
	v_mov_b32_dpp v196, v95 row_ror:15 row_mask:0xf bank_mask:0xf
	v_mov_b32_dpp v187, v87 row_ror:1 row_mask:0xf bank_mask:0xf
	v_mov_b32_dpp v194, v87 row_ror:15 row_mask:0xf bank_mask:0xf
	v_mov_b32_dpp v134, v83 row_ror:1 row_mask:0xf bank_mask:0xf
	v_mov_b32_dpp v189, v83 row_ror:15 row_mask:0xf bank_mask:0xf
	v_mov_b32_dpp v135, v71 row_ror:1 row_mask:0xf bank_mask:0xf
	v_mov_b32_dpp v129, v71 row_ror:15 row_mask:0xf bank_mask:0xf
	v_lshlrev_b32_e32 v107, 16, v132
	v_lshlrev_b32_e32 v106, 16, v130
	v_and_b32_e32 v109, 0xffff0000, v132
	v_and_b32_e32 v108, 0xffff0000, v130
	v_lshlrev_b32_e32 v111, 16, v133
	v_lshlrev_b32_e32 v110, 16, v131
	v_and_b32_e32 v113, 0xffff0000, v133
	v_and_b32_e32 v112, 0xffff0000, v131
	v_mov_b32_dpp v120, v96 row_ror:1 row_mask:0xf bank_mask:0xf
	v_mov_b32_dpp v197, v96 row_ror:15 row_mask:0xf bank_mask:0xf
	v_mov_b32_dpp v174, v88 row_ror:1 row_mask:0xf bank_mask:0xf
	v_mov_b32_dpp v188, v88 row_ror:15 row_mask:0xf bank_mask:0xf
	v_mov_b32_dpp v131, v84 row_ror:1 row_mask:0xf bank_mask:0xf
	v_mov_b32_dpp v175, v84 row_ror:15 row_mask:0xf bank_mask:0xf
	v_mov_b32_dpp v132, v72 row_ror:1 row_mask:0xf bank_mask:0xf
	v_mov_b32_dpp v130, v72 row_ror:15 row_mask:0xf bank_mask:0xf
	v_mov_b32_dpp v121, v97 row_ror:1 row_mask:0xf bank_mask:0xf
	v_mov_b32_dpp v198, v97 row_ror:15 row_mask:0xf bank_mask:0xf
	v_mov_b32_dpp v172, v89 row_ror:1 row_mask:0xf bank_mask:0xf
	v_mov_b32_dpp v192, v89 row_ror:15 row_mask:0xf bank_mask:0xf
	v_mov_b32_dpp v136, v85 row_ror:1 row_mask:0xf bank_mask:0xf
	v_mov_b32_dpp v173, v85 row_ror:15 row_mask:0xf bank_mask:0xf
	v_mov_b32_dpp v137, v73 row_ror:1 row_mask:0xf bank_mask:0xf
	v_mov_b32_dpp v133, v73 row_ror:15 row_mask:0xf bank_mask:0xf
	s_and_saveexec_b64 s[38:39], s[4:5]
	s_cbranch_execz .LBB0_1543
	v_fma_f32 v200, v106, v120, v112
	v_fma_f32 v201, v107, v121, v113
	v_cndmask_b32_e64 v199, v198, v192, s[6:7]
	v_fma_f32 v200, v96, v108, v200
	v_fma_f32 v201, v97, v109, v201
	v_cndmask_b32_e64 v198, v197, v188, s[6:7]
	v_fma_f32 v198, v198, v110, v200
	v_fma_f32 v199, v199, v111, v201
	v_cndmask_b32_e64 v203, v196, v194, s[6:7]
	v_mul_f32_e32 v200, 0xbfb8aa3b, v198
	v_exp_f32_e32 v200, v200
	v_cndmask_b32_e64 v202, v195, v193, s[6:7]
	v_mul_f32_e32 v197, 0xbfb8aa3b, v199
	v_exp_f32_e32 v197, v197
	v_add_f32_e32 v204, 1.0, v200
	v_fma_f32 v200, v98, v122, v104
	v_fma_f32 v201, v99, v123, v105
	v_add_f32_e32 v197, 1.0, v197
	v_fma_f32 v200, v94, v100, v200
	v_fma_f32 v201, v95, v101, v201
	v_rcp_f32_e32 v197, v197
	v_fma_f32 v200, v202, v102, v200
	v_fma_f32 v201, v203, v103, v201
	s_nop 0
	v_mul_f32_e32 v195, 0xbfb8aa3b, v201
	v_exp_f32_e32 v195, v195
	v_mul_f32_e32 v196, 0xbfb8aa3b, v200
	v_exp_f32_e32 v202, v196
	v_rcp_f32_e32 v196, v204
	v_add_f32_e32 v195, 1.0, v195
	v_rcp_f32_e32 v203, v195
	v_add_f32_e32 v195, 1.0, v202
	v_rcp_f32_e32 v202, v195
	v_mul_f32_e32 v196, v198, v196
	v_mul_f32_e32 v197, v199, v197
	v_mul_f32_e32 v198, v200, v202
	v_mul_f32_e32 v199, v201, v203
	v_mul_f32_e32 v196, v92, v196
	v_mul_f32_e32 v197, v93, v197
	v_mul_f32_e32 v198, v90, v198
	v_mul_f32_e32 v199, v91, v199
	s_nop 0
	v_cvt_pk_bf16_f32 v198, v198, v199
	v_cvt_pk_bf16_f32 v199, v196, v197
	v_mov_b64_e32 v[196:197], s[18:19]
	v_mad_i64_i32 v[196:197], s[42:43], v185, s65, v[196:197]
	v_lshl_add_u64 v[196:197], v[154:155], 1, v[196:197]
	global_store_dwordx2 v[196:197], v[198:199], off offset:8

; #define GAS __attribute__((address_space(1)))
; __device__ __forceinline__ unsigned pk2(float lo, float hi) { const f32x2cv v = {lo, hi}; return __builtin_bit_cast(unsigned, __builtin_convertvector(v, bf16x2cv)); }
;     __device__ __forceinline__ void operator()(const pg8::f32x4 (&acc)[2][2][4][2], const pg8::Unit& u, int wr, int wc, int fr, int fq) const {
;     ...
;                 const int hc = hc0 + 4 * n;
;                 float out[4][4];
; #pragma unroll
;                 for (int e = 0; e < 4; ++e) { const int c = 4 * n + e; const unsigned pw0 = (c & 1) ? wq[c >> 1].z : wq[c >> 1].x, pw1 = (c & 1) ? wq[c >> 1].w : wq[c >> 1].y;
;                     const float w0 = bflo(pw0), w1 = bfhi(pw0), w2 = bflo(pw1), b0 = bfhi(pw1);
;                     float a[4], up[4], dn[4];
; #pragma unroll
;                     for (int m = 0; m < 4; ++m) { a[m] = acc[ai][0][m][n][e];
;                         up[m] = __builtin_bit_cast(float, __builtin_amdgcn_mov_dpp(__builtin_bit_cast(int, a[m]), 0x121, 0xf, 0xf, false));
;                         dn[m] = __builtin_bit_cast(float, __builtin_amdgcn_mov_dpp(__builtin_bit_cast(int, a[m]), 0x12f, 0xf, 0xf, false)); }
; #pragma unroll
;                     for (int m = 0; m < 4; ++m) { const float prev = fr > 0 ? up[m] : (m > 0 ? up[m > 0 ? m - 1 : 0] : 0.f), next = fr < 15 ? dn[m] : (m < 3 ? dn[m < 3 ? m + 1 : 3] : 0.f);
;                         const float cv = b0 + w0 * prev + w1 * a[m] + w2 * next; out[m][e] = siluf_(cv) * acc[ai][1][m][n][e]; } }
; #pragma unroll
;                 for (int m = 0; m < 4; ++m) { const int r64 = 16 * m + fr, row = rowbase + r64;
;                     if (r64 != 0 && r64 != 63) { v2u w; w.x = pk2(out[m][0], out[m][1]); w.y = pk2(out[m][2], out[m][3]); *(GAS v2u*)(hg + (size_t)row * FFH + hc) = w; }
;                     if (r64 <= 1 || r64 >= 62) { const int slot = r64 <= 1 ? r64 : r64 - 60; const f32x4 ra = acc[ai][0][m][n];
;                         v2u w; w.x = pk2(ra[0], ra[1]); w.y = pk2(ra[2], ra[3]); *(GAS v2u*)(ab + (size_t)(g64 * 4 + slot) * FFH + hc) = w;
;                         if (r64 == 0 || r64 == 63) { const f32x4 rg = acc[ai][1][m][n]; v2u wg; wg.x = pk2(rg[0], rg[1]); wg.y = pk2(rg[2], rg[3]); *(GAS v2u*)(gb + (size_t)(g64 * 2 + (r64 == 63 ? 1 : 0)) * FFH + hc) = wg; } }
.LBB0_1546:
	s_or_b64 exec, exec, s[38:39]
	v_cndmask_b32_e64 v91, v187, v123, s[2:3]
	v_cndmask_b32_e64 v90, v190, v122, s[2:3]
	v_fma_f32 v90, v90, v98, v104
	v_fma_f32 v91, v91, v99, v105
	v_cndmask_b32_e64 v93, v194, v189, s[6:7]
	v_cndmask_b32_e64 v92, v193, v191, s[6:7]
	v_fma_f32 v86, v86, v100, v90
	v_fma_f32 v87, v87, v101, v91
	v_cndmask_b32_e64 v94, v189, v129, s[6:7]
	v_fma_f32 v86, v92, v102, v86
	v_fma_f32 v87, v93, v103, v87
	v_cndmask_b32_e64 v92, v127, v190, s[2:3]
	v_mul_f32_e32 v90, 0xbfb8aa3b, v86
	v_mul_f32_e32 v91, 0xbfb8aa3b, v87
	v_fma_f32 v92, v98, v92, v104
	v_exp_f32_e32 v90, v90
	v_exp_f32_e32 v91, v91
	v_cndmask_b32_e64 v93, v191, v126, s[6:7]
	v_fmac_f32_e32 v92, v82, v100
	v_fmac_f32_e32 v92, v102, v93
	v_mul_f32_e32 v82, 0xbfb8aa3b, v92
	v_exp_f32_e32 v93, v82
	v_cndmask_b32_e64 v82, v134, v187, s[2:3]
	v_add_f32_e32 v90, 1.0, v90
	v_add_f32_e32 v91, 1.0, v91
	v_fma_f32 v95, v99, v82, v105
	v_rcp_f32_e32 v90, v90
	v_rcp_f32_e32 v91, v91
	v_fmac_f32_e32 v95, v83, v101
	v_fmac_f32_e32 v95, v103, v94
	v_mul_f32_e32 v82, 0xbfb8aa3b, v95
	v_exp_f32_e32 v94, v82
	v_mul_f32_e32 v82, v86, v90
	v_mul_f32_e32 v83, v87, v91
	v_add_f32_e32 v86, 1.0, v93
	v_rcp_f32_e32 v86, v86
	v_add_f32_e32 v87, 1.0, v94
	v_rcp_f32_e32 v87, v87
	v_mul_f32_e32 v78, v78, v82
	v_mul_f32_e32 v79, v79, v83
	v_mul_f32_e32 v82, v92, v86
	v_mul_f32_e32 v90, v74, v82
	v_cndmask_b32_e64 v83, v172, v121, s[2:3]
	v_cndmask_b32_e64 v82, v174, v120, s[2:3]
	v_fma_f32 v82, v82, v106, v112
	v_fma_f32 v83, v83, v107, v113
	v_mul_f32_e32 v74, v95, v87
	v_cndmask_b32_e64 v87, v192, v173, s[6:7]
	v_cndmask_b32_e64 v86, v188, v175, s[6:7]
	v_fma_f32 v82, v88, v108, v82
	v_fma_f32 v83, v89, v109, v83
	v_mul_f32_e32 v88, v75, v74
	v_fma_f32 v82, v86, v110, v82
	v_fma_f32 v83, v87, v111, v83
	v_cndmask_b32_e64 v89, v173, v133, s[6:7]
	v_mul_f32_e32 v86, 0xbfb8aa3b, v82
	v_exp_f32_e32 v86, v86
	v_mul_f32_e32 v87, 0xbfb8aa3b, v83
	v_exp_f32_e32 v87, v87
	v_add_f32_e32 v74, 1.0, v86
	v_cndmask_b32_e64 v86, v131, v174, s[2:3]
	v_fma_f32 v86, v106, v86, v112
	v_add_f32_e32 v75, 1.0, v87
	v_cndmask_b32_e64 v87, v175, v130, s[6:7]
	v_fmac_f32_e32 v86, v84, v108
	v_fmac_f32_e32 v86, v110, v87
	v_cndmask_b32_e64 v87, v136, v172, s[2:3]
	v_fma_f32 v87, v107, v87, v113
	v_fmac_f32_e32 v87, v85, v109
	v_mul_f32_e32 v84, 0xbfb8aa3b, v86
	v_fmac_f32_e32 v87, v111, v89
	v_rcp_f32_e32 v74, v74
	v_rcp_f32_e32 v75, v75
	v_exp_f32_e32 v84, v84
	v_mul_f32_e32 v85, 0xbfb8aa3b, v87
	v_exp_f32_e32 v85, v85
	v_mul_f32_e32 v74, v82, v74
	v_mul_f32_e32 v75, v83, v75
	v_add_f32_e32 v82, 1.0, v84
	v_rcp_f32_e32 v82, v82
	v_add_f32_e32 v83, 1.0, v85
	v_rcp_f32_e32 v83, v83
	v_mul_f32_e32 v74, v80, v74
	v_mul_f32_e32 v75, v81, v75
	v_mul_f32_e32 v80, v86, v82
	v_mul_f32_e32 v80, v76, v80
	v_mul_f32_e32 v76, v87, v83
	v_mul_f32_e32 v81, v77, v76
	v_cvt_pk_bf16_f32 v76, v78, v79
	v_cvt_pk_bf16_f32 v77, v74, v75
	v_cvt_pk_bf16_f32 v74, v90, v88
	v_cvt_pk_bf16_f32 v75, v80, v81
	global_store_dwordx2 v[116:117], v[76:77], off offset:8
	global_store_dwordx2 v[118:119], v[74:75], off offset:8
	s_and_saveexec_b64 s[38:39], s[8:9]
	s_cbranch_execz .LBB0_1548
	v_cndmask_b32_e64 v74, v128, v127, s[2:3]
	v_cndmask_b32_e64 v75, v135, v134, s[2:3]
	v_cndmask_b32_e64 v78, v132, v131, s[2:3]
	v_cndmask_b32_e64 v79, v137, v136, s[2:3]
	v_fma_f32 v74, v74, v98, v104
	v_fma_f32 v75, v75, v99, v105
	v_fma_f32 v78, v78, v106, v112
	v_fma_f32 v79, v79, v107, v113
	v_cndmask_b32_e64 v76, v126, 0, s[6:7]
	v_cndmask_b32_e64 v77, v129, 0, s[6:7]
	v_fma_f32 v74, v70, v100, v74
	v_fma_f32 v75, v71, v101, v75
	v_cndmask_b32_e64 v80, v130, 0, s[6:7]
	v_cndmask_b32_e64 v81, v133, 0, s[6:7]
	v_fma_f32 v78, v72, v108, v78
	v_fma_f32 v79, v73, v109, v79
	v_fma_f32 v74, v76, v102, v74
	v_fma_f32 v75, v77, v103, v75
	v_fma_f32 v78, v80, v110, v78
	v_fma_f32 v79, v81, v111, v79
	v_mul_f32_e32 v76, 0xbfb8aa3b, v74
	v_mul_f32_e32 v77, 0xbfb8aa3b, v75
	v_mul_f32_e32 v80, 0xbfb8aa3b, v78
	v_mul_f32_e32 v81, 0xbfb8aa3b, v79
	v_exp_f32_e32 v76, v76
	v_exp_f32_e32 v77, v77
	v_exp_f32_e32 v80, v80
	v_exp_f32_e32 v81, v81
	v_add_f32_e32 v76, 1.0, v76
	v_add_f32_e32 v77, 1.0, v77
	v_add_f32_e32 v80, 1.0, v80
	v_add_f32_e32 v81, 1.0, v81
	v_rcp_f32_e32 v76, v76
	v_rcp_f32_e32 v77, v77
	v_rcp_f32_e32 v80, v80
	v_rcp_f32_e32 v81, v81
	v_mul_f32_e32 v74, v74, v76
	v_mul_f32_e32 v75, v75, v77
	s_nop 0
	v_mul_f32_e32 v74, v66, v74
	v_mul_f32_e32 v75, v67, v75
	v_mul_f32_e32 v76, v78, v80
	v_mul_f32_e32 v77, v79, v81
	v_cvt_pk_bf16_f32 v74, v74, v75
	v_mul_f32_e32 v76, v68, v76
	v_mul_f32_e32 v77, v69, v77
	s_nop 0
	v_cvt_pk_bf16_f32 v75, v76, v77
	v_mov_b64_e32 v[76:77], s[18:19]
	v_mad_i64_i32 v[76:77], s[42:43], v124, s65, v[76:77]
	v_lshl_add_u64 v[76:77], v[154:155], 1, v[76:77]
	global_store_dwordx2 v[76:77], v[74:75], off offset:8

; #define GAS __attribute__((address_space(1)))
; __device__ __forceinline__ unsigned pk2(float lo, float hi) { const f32x2cv v = {lo, hi}; return __builtin_bit_cast(unsigned, __builtin_convertvector(v, bf16x2cv)); }
; __device__ __forceinline__ float siluf_(float x) { return x * __builtin_amdgcn_rcpf(1.0f + __builtin_amdgcn_exp2f(-1.4426950408889634f * x)); }
;     __device__ __forceinline__ void operator()(const pg8::f32x4 (&acc)[2][2][4][2], const pg8::Unit& u, int wr, int wc, int fr, int fq) const {
;     ...
;                 const int hc = hc0 + 4 * n;
;                 float out[4][4];
; #pragma unroll
;                 for (int e = 0; e < 4; ++e) { const int c = 4 * n + e; const unsigned pw0 = (c & 1) ? wq[c >> 1].z : wq[c >> 1].x, pw1 = (c & 1) ? wq[c >> 1].w : wq[c >> 1].y;
;                     const float w0 = bflo(pw0), w1 = bfhi(pw0), w2 = bflo(pw1), b0 = bfhi(pw1);
;                     float a[4], up[4], dn[4];
; #pragma unroll
;                     for (int m = 0; m < 4; ++m) { a[m] = acc[ai][0][m][n][e];
;                         up[m] = __builtin_bit_cast(float, __builtin_amdgcn_mov_dpp(__builtin_bit_cast(int, a[m]), 0x121, 0xf, 0xf, false));
;                         dn[m] = __builtin_bit_cast(float, __builtin_amdgcn_mov_dpp(__builtin_bit_cast(int, a[m]), 0x12f, 0xf, 0xf, false)); }
; #pragma unroll
;                     for (int m = 0; m < 4; ++m) { const float prev = fr > 0 ? up[m] : (m > 0 ? up[m > 0 ? m - 1 : 0] : 0.f), next = fr < 15 ? dn[m] : (m < 3 ? dn[m < 3 ? m + 1 : 3] : 0.f);
;                         const float cv = b0 + w0 * prev + w1 * a[m] + w2 * next; out[m][e] = siluf_(cv) * acc[ai][1][m][n][e]; } }
; #pragma unroll
;                 for (int m = 0; m < 4; ++m) { const int r64 = 16 * m + fr, row = rowbase + r64;
;                     if (r64 != 0 && r64 != 63) { v2u w; w.x = pk2(out[m][0], out[m][1]); w.y = pk2(out[m][2], out[m][3]); *(GAS v2u*)(hg + (size_t)row * FFH + hc) = w; }
.LBB0_1551:
	s_or_b64 exec, exec, s[38:39]
	s_add_i32 s31, s29, 0x80
	v_mov_b32_dpp v68, v62 row_ror:1 row_mask:0xf bank_mask:0xf
	v_mov_b32_dpp v71, v62 row_ror:15 row_mask:0xf bank_mask:0xf
	v_mov_b32_dpp v92, v54 row_ror:1 row_mask:0xf bank_mask:0xf
	v_mov_b32_dpp v94, v54 row_ror:15 row_mask:0xf bank_mask:0xf
	v_mov_b32_dpp v77, v50 row_ror:1 row_mask:0xf bank_mask:0xf
	v_mov_b32_dpp v93, v50 row_ror:15 row_mask:0xf bank_mask:0xf
	v_mov_b32_dpp v79, v38 row_ror:1 row_mask:0xf bank_mask:0xf
	v_mov_b32_dpp v75, v38 row_ror:15 row_mask:0xf bank_mask:0xf
	v_mov_b32_dpp v69, v63 row_ror:1 row_mask:0xf bank_mask:0xf
	v_mov_b32_dpp v96, v63 row_ror:15 row_mask:0xf bank_mask:0xf
	v_mov_b32_dpp v90, v55 row_ror:1 row_mask:0xf bank_mask:0xf
	v_mov_b32_dpp v95, v55 row_ror:15 row_mask:0xf bank_mask:0xf
	v_mov_b32_dpp v82, v51 row_ror:1 row_mask:0xf bank_mask:0xf
	v_mov_b32_dpp v91, v51 row_ror:15 row_mask:0xf bank_mask:0xf
	v_mov_b32_dpp v83, v39 row_ror:1 row_mask:0xf bank_mask:0xf
	v_mov_b32_dpp v81, v39 row_ror:15 row_mask:0xf bank_mask:0xf
	v_mov_b32_dpp v66, v64 row_ror:1 row_mask:0xf bank_mask:0xf
	v_mov_b32_dpp v97, v64 row_ror:15 row_mask:0xf bank_mask:0xf
	v_mov_b32_dpp v86, v56 row_ror:1 row_mask:0xf bank_mask:0xf
	v_mov_b32_dpp v88, v56 row_ror:15 row_mask:0xf bank_mask:0xf
	v_mov_b32_dpp v73, v52 row_ror:1 row_mask:0xf bank_mask:0xf
	v_mov_b32_dpp v87, v52 row_ror:15 row_mask:0xf bank_mask:0xf
	v_mov_b32_dpp v74, v40 row_ror:1 row_mask:0xf bank_mask:0xf
	v_mov_b32_dpp v72, v40 row_ror:15 row_mask:0xf bank_mask:0xf
	v_mov_b32_dpp v67, v65 row_ror:1 row_mask:0xf bank_mask:0xf
	v_mov_b32_dpp v116, v65 row_ror:15 row_mask:0xf bank_mask:0xf
	v_mov_b32_dpp v84, v57 row_ror:1 row_mask:0xf bank_mask:0xf
	v_mov_b32_dpp v89, v57 row_ror:15 row_mask:0xf bank_mask:0xf
	v_mov_b32_dpp v78, v53 row_ror:1 row_mask:0xf bank_mask:0xf
	v_mov_b32_dpp v85, v53 row_ror:15 row_mask:0xf bank_mask:0xf
	v_mov_b32_dpp v80, v41 row_ror:1 row_mask:0xf bank_mask:0xf
	v_mov_b32_dpp v76, v41 row_ror:15 row_mask:0xf bank_mask:0xf
	v_or_b32_e32 v70, s31, v1
	s_and_saveexec_b64 s[38:39], s[4:5]
	s_cbranch_execz .LBB0_1553
	v_fma_f32 v118, v156, v66, v158
	v_fma_f32 v119, v157, v67, v159
	v_cndmask_b32_e64 v117, v116, v89, s[6:7]
	v_fma_f32 v118, v64, v160, v118
	v_fma_f32 v119, v65, v161, v119
	v_cndmask_b32_e64 v116, v97, v88, s[6:7]
	v_fma_f32 v116, v116, v162, v118
	v_fma_f32 v117, v117, v163, v119
	v_cndmask_b32_e64 v121, v96, v95, s[6:7]
	v_mul_f32_e32 v118, 0xbfb8aa3b, v116
	v_exp_f32_e32 v118, v118
	v_cndmask_b32_e64 v120, v71, v94, s[6:7]
	v_mul_f32_e32 v97, 0xbfb8aa3b, v117
	v_exp_f32_e32 v97, v97
	v_add_f32_e32 v122, 1.0, v118
	v_fma_f32 v118, v164, v68, v166
	v_fma_f32 v119, v165, v69, v167
	v_add_f32_e32 v97, 1.0, v97
	v_fma_f32 v118, v62, v168, v118
	v_fma_f32 v119, v63, v169, v119
	v_rcp_f32_e32 v97, v97
	v_fma_f32 v118, v120, v170, v118
	v_fma_f32 v119, v121, v171, v119
	s_nop 0
	v_mul_f32_e32 v71, 0xbfb8aa3b, v119
	v_exp_f32_e32 v71, v71
	v_mul_f32_e32 v96, 0xbfb8aa3b, v118
	v_exp_f32_e32 v120, v96
	v_rcp_f32_e32 v96, v122
	v_add_f32_e32 v71, 1.0, v71
	v_rcp_f32_e32 v121, v71
	v_add_f32_e32 v71, 1.0, v120
	v_rcp_f32_e32 v120, v71
	v_mul_f32_e32 v96, v116, v96
	v_mul_f32_e32 v97, v117, v97
	v_mul_f32_e32 v116, v118, v120
	v_mul_f32_e32 v117, v119, v121
	v_mul_f32_e32 v96, v60, v96
	v_mul_f32_e32 v97, v61, v97
	v_mul_f32_e32 v116, v58, v116
	v_mul_f32_e32 v117, v59, v117
	s_nop 0
	v_cvt_pk_bf16_f32 v116, v116, v117
	v_cvt_pk_bf16_f32 v117, v96, v97
	v_mov_b64_e32 v[96:97], s[18:19]
	v_mad_i64_i32 v[96:97], s[42:43], v70, s65, v[96:97]
	v_lshl_add_u64 v[96:97], v[154:155], 1, v[96:97]
	global_store_dwordx2 v[96:97], v[116:117], off

; #define GAS __attribute__((address_space(1)))
; __device__ __forceinline__ unsigned pk2(float lo, float hi) { const f32x2cv v = {lo, hi}; return __builtin_bit_cast(unsigned, __builtin_convertvector(v, bf16x2cv)); }
;     __device__ __forceinline__ void operator()(const pg8::f32x4 (&acc)[2][2][4][2], const pg8::Unit& u, int wr, int wc, int fr, int fq) const {
;     ...
;                 const int hc = hc0 + 4 * n;
;                 float out[4][4];
; #pragma unroll
;                 for (int e = 0; e < 4; ++e) { const int c = 4 * n + e; const unsigned pw0 = (c & 1) ? wq[c >> 1].z : wq[c >> 1].x, pw1 = (c & 1) ? wq[c >> 1].w : wq[c >> 1].y;
;                     const float w0 = bflo(pw0), w1 = bfhi(pw0), w2 = bflo(pw1), b0 = bfhi(pw1);
;                     float a[4], up[4], dn[4];
; #pragma unroll
;                     for (int m = 0; m < 4; ++m) { a[m] = acc[ai][0][m][n][e];
;                         up[m] = __builtin_bit_cast(float, __builtin_amdgcn_mov_dpp(__builtin_bit_cast(int, a[m]), 0x121, 0xf, 0xf, false));
;                         dn[m] = __builtin_bit_cast(float, __builtin_amdgcn_mov_dpp(__builtin_bit_cast(int, a[m]), 0x12f, 0xf, 0xf, false)); }
; #pragma unroll
;                     for (int m = 0; m < 4; ++m) { const float prev = fr > 0 ? up[m] : (m > 0 ? up[m > 0 ? m - 1 : 0] : 0.f), next = fr < 15 ? dn[m] : (m < 3 ? dn[m < 3 ? m + 1 : 3] : 0.f);
;                         const float cv = b0 + w0 * prev + w1 * a[m] + w2 * next; out[m][e] = siluf_(cv) * acc[ai][1][m][n][e]; } }
; #pragma unroll
;                 for (int m = 0; m < 4; ++m) { const int r64 = 16 * m + fr, row = rowbase + r64;
;                     if (r64 != 0 && r64 != 63) { v2u w; w.x = pk2(out[m][0], out[m][1]); w.y = pk2(out[m][2], out[m][3]); *(GAS v2u*)(hg + (size_t)row * FFH + hc) = w; }
;                     if (r64 <= 1 || r64 >= 62) { const int slot = r64 <= 1 ? r64 : r64 - 60; const f32x4 ra = acc[ai][0][m][n];
;                         v2u w; w.x = pk2(ra[0], ra[1]); w.y = pk2(ra[2], ra[3]); *(GAS v2u*)(ab + (size_t)(g64 * 4 + slot) * FFH + hc) = w;
;                         if (r64 == 0 || r64 == 63) { const f32x4 rg = acc[ai][1][m][n]; v2u wg; wg.x = pk2(rg[0], rg[1]); wg.y = pk2(rg[2], rg[3]); *(GAS v2u*)(gb + (size_t)(g64 * 2 + (r64 == 63 ? 1 : 0)) * FFH + hc) = wg; } }
.LBB0_1556:
	s_or_b64 exec, exec, s[38:39]
	v_cndmask_b32_e64 v59, v90, v69, s[2:3]
	v_cndmask_b32_e64 v58, v92, v68, s[2:3]
	v_fma_f32 v58, v58, v164, v166
	v_fma_f32 v59, v59, v165, v167
	v_cndmask_b32_e64 v61, v95, v91, s[6:7]
	v_cndmask_b32_e64 v60, v94, v93, s[6:7]
	v_fma_f32 v54, v54, v168, v58
	v_fma_f32 v55, v55, v169, v59
	v_cndmask_b32_e64 v62, v91, v81, s[6:7]
	v_fma_f32 v54, v60, v170, v54
	v_fma_f32 v55, v61, v171, v55
	v_cndmask_b32_e64 v60, v77, v92, s[2:3]
	v_mul_f32_e32 v58, 0xbfb8aa3b, v54
	v_mul_f32_e32 v59, 0xbfb8aa3b, v55
	v_fma_f32 v60, v164, v60, v166
	v_exp_f32_e32 v58, v58
	v_exp_f32_e32 v59, v59
	v_cndmask_b32_e64 v61, v93, v75, s[6:7]
	v_fmac_f32_e32 v60, v50, v168
	v_fmac_f32_e32 v60, v170, v61
	v_mul_f32_e32 v50, 0xbfb8aa3b, v60
	v_exp_f32_e32 v61, v50
	v_cndmask_b32_e64 v50, v82, v90, s[2:3]
	v_add_f32_e32 v58, 1.0, v58
	v_add_f32_e32 v59, 1.0, v59
	v_fma_f32 v63, v165, v50, v167
	v_rcp_f32_e32 v58, v58
	v_rcp_f32_e32 v59, v59
	v_fmac_f32_e32 v63, v51, v169
	v_fmac_f32_e32 v63, v171, v62
	v_mul_f32_e32 v50, 0xbfb8aa3b, v63
	v_exp_f32_e32 v62, v50
	v_mul_f32_e32 v50, v54, v58
	v_mul_f32_e32 v51, v55, v59
	v_add_f32_e32 v54, 1.0, v61
	v_rcp_f32_e32 v54, v54
	v_add_f32_e32 v55, 1.0, v62
	v_rcp_f32_e32 v55, v55
	v_mul_f32_e32 v46, v46, v50
	v_mul_f32_e32 v47, v47, v51
	v_mul_f32_e32 v50, v60, v54
	v_mul_f32_e32 v58, v42, v50
	v_cndmask_b32_e64 v51, v84, v67, s[2:3]
	v_cndmask_b32_e64 v50, v86, v66, s[2:3]
	v_fma_f32 v50, v50, v156, v158
	v_fma_f32 v51, v51, v157, v159
	v_mul_f32_e32 v42, v63, v55
	v_cndmask_b32_e64 v55, v89, v85, s[6:7]
	v_cndmask_b32_e64 v54, v88, v87, s[6:7]
	v_fma_f32 v50, v56, v160, v50
	v_fma_f32 v51, v57, v161, v51
	v_mul_f32_e32 v56, v43, v42
	v_fma_f32 v50, v54, v162, v50
	v_fma_f32 v51, v55, v163, v51
	v_cndmask_b32_e64 v57, v85, v76, s[6:7]
	v_mul_f32_e32 v54, 0xbfb8aa3b, v50
	v_exp_f32_e32 v54, v54
	v_mul_f32_e32 v55, 0xbfb8aa3b, v51
	v_exp_f32_e32 v55, v55
	v_add_f32_e32 v42, 1.0, v54
	v_cndmask_b32_e64 v54, v73, v86, s[2:3]
	v_fma_f32 v54, v156, v54, v158
	v_add_f32_e32 v43, 1.0, v55
	v_cndmask_b32_e64 v55, v87, v72, s[6:7]
	v_fmac_f32_e32 v54, v52, v160
	v_fmac_f32_e32 v54, v162, v55
	v_cndmask_b32_e64 v55, v78, v84, s[2:3]
	v_fma_f32 v55, v157, v55, v159
	v_fmac_f32_e32 v55, v53, v161
	v_mul_f32_e32 v52, 0xbfb8aa3b, v54
	v_fmac_f32_e32 v55, v163, v57
	v_rcp_f32_e32 v42, v42
	v_rcp_f32_e32 v43, v43
	v_exp_f32_e32 v52, v52
	v_mul_f32_e32 v53, 0xbfb8aa3b, v55
	v_exp_f32_e32 v53, v53
	v_mul_f32_e32 v42, v50, v42
	v_mul_f32_e32 v43, v51, v43
	v_add_f32_e32 v50, 1.0, v52
	v_rcp_f32_e32 v50, v50
	v_add_f32_e32 v51, 1.0, v53
	v_rcp_f32_e32 v51, v51
	v_mul_f32_e32 v42, v48, v42
	v_mul_f32_e32 v43, v49, v43
	v_mul_f32_e32 v48, v54, v50
	v_mul_f32_e32 v49, v44, v48
	v_mul_f32_e32 v44, v55, v51
	v_mul_f32_e32 v50, v45, v44
	v_or_b32_e32 v48, s31, v177
	v_cvt_pk_bf16_f32 v44, v46, v47
	v_mov_b64_e32 v[46:47], s[18:19]
	v_cvt_pk_bf16_f32 v45, v42, v43
	v_mad_i64_i32 v[42:43], s[38:39], v48, s65, v[46:47]
	v_lshl_add_u64 v[42:43], v[42:43], 0, v[114:115]
	global_store_dwordx2 v[42:43], v[44:45], off
	v_or_b32_e32 v44, s31, v178
	v_mad_i64_i32 v[44:45], s[38:39], v44, s65, v[46:47]
	v_cvt_pk_bf16_f32 v48, v58, v56
	v_cvt_pk_bf16_f32 v49, v49, v50
	v_lshl_add_u64 v[44:45], v[44:45], 0, v[114:115]
	v_or_b32_e32 v46, s31, v179
	global_store_dwordx2 v[44:45], v[48:49], off
	s_and_saveexec_b64 s[38:39], s[8:9]
	s_cbranch_execz .LBB0_1558
	v_cndmask_b32_e64 v48, v79, v77, s[2:3]
	v_cndmask_b32_e64 v49, v83, v82, s[2:3]
	v_fma_f32 v48, v48, v164, v166
	v_fma_f32 v49, v49, v165, v167
	v_cndmask_b32_e64 v50, v75, 0, s[6:7]
	v_cndmask_b32_e64 v51, v81, 0, s[6:7]
	v_fma_f32 v48, v38, v168, v48
	v_fma_f32 v49, v39, v169, v49
	v_cndmask_b32_e64 v52, v74, v73, s[2:3]
	v_fma_f32 v48, v50, v170, v48
	v_fma_f32 v49, v51, v171, v49
	v_cndmask_b32_e64 v53, v80, v78, s[2:3]
	v_mul_f32_e32 v47, 0xbfb8aa3b, v48
	v_exp_f32_e32 v47, v47
	v_mul_f32_e32 v50, 0xbfb8aa3b, v49
	v_exp_f32_e32 v51, v50
	v_fma_f32 v52, v52, v156, v158
	v_fma_f32 v53, v53, v157, v159
	v_cndmask_b32_e64 v54, v72, 0, s[6:7]
	v_cndmask_b32_e64 v55, v76, 0, s[6:7]
	v_fma_f32 v52, v40, v160, v52
	v_fma_f32 v53, v41, v161, v53
	v_add_f32_e32 v47, 1.0, v47
	v_fma_f32 v52, v54, v162, v52
	v_fma_f32 v53, v55, v163, v53
	v_rcp_f32_e32 v50, v47
	v_add_f32_e32 v47, 1.0, v51
	v_mul_f32_e32 v51, 0xbfb8aa3b, v52
	v_exp_f32_e32 v54, v51
	v_mul_f32_e32 v51, 0xbfb8aa3b, v53
	v_exp_f32_e32 v55, v51
	v_rcp_f32_e32 v51, v47
	v_add_f32_e32 v47, 1.0, v54
	v_rcp_f32_e32 v54, v47
	v_add_f32_e32 v47, 1.0, v55
	v_rcp_f32_e32 v55, v47
	v_mul_f32_e32 v48, v48, v50
	v_mul_f32_e32 v49, v49, v51
	v_mul_f32_e32 v50, v52, v54
	v_mul_f32_e32 v51, v53, v55
	v_mul_f32_e32 v48, v34, v48
	v_mul_f32_e32 v49, v35, v49
	v_mul_f32_e32 v50, v36, v50
	v_mul_f32_e32 v51, v37, v51
	v_cvt_pk_bf16_f32 v48, v48, v49
	v_cvt_pk_bf16_f32 v49, v50, v51
	v_mov_b64_e32 v[50:51], s[18:19]
	v_mad_i64_i32 v[50:51], s[42:43], v46, s65, v[50:51]
	v_lshl_add_u64 v[50:51], v[154:155], 1, v[50:51]
	global_store_dwordx2 v[50:51], v[48:49], off

; #define GAS __attribute__((address_space(1)))
; __device__ __forceinline__ unsigned pk2(float lo, float hi) { const f32x2cv v = {lo, hi}; return __builtin_bit_cast(unsigned, __builtin_convertvector(v, bf16x2cv)); }
; __device__ __forceinline__ float siluf_(float x) { return x * __builtin_amdgcn_rcpf(1.0f + __builtin_amdgcn_exp2f(-1.4426950408889634f * x)); }
;     __device__ __forceinline__ void operator()(const pg8::f32x4 (&acc)[2][2][4][2], const pg8::Unit& u, int wr, int wc, int fr, int fq) const {
;     ...
;                 const int hc = hc0 + 4 * n;
;                 float out[4][4];
; #pragma unroll
;                 for (int e = 0; e < 4; ++e) { const int c = 4 * n + e; const unsigned pw0 = (c & 1) ? wq[c >> 1].z : wq[c >> 1].x, pw1 = (c & 1) ? wq[c >> 1].w : wq[c >> 1].y;
;                     const float w0 = bflo(pw0), w1 = bfhi(pw0), w2 = bflo(pw1), b0 = bfhi(pw1);
;                     float a[4], up[4], dn[4];
; #pragma unroll
;                     for (int m = 0; m < 4; ++m) { a[m] = acc[ai][0][m][n][e];
;                         up[m] = __builtin_bit_cast(float, __builtin_amdgcn_mov_dpp(__builtin_bit_cast(int, a[m]), 0x121, 0xf, 0xf, false));
;                         dn[m] = __builtin_bit_cast(float, __builtin_amdgcn_mov_dpp(__builtin_bit_cast(int, a[m]), 0x12f, 0xf, 0xf, false)); }
; #pragma unroll
;                     for (int m = 0; m < 4; ++m) { const float prev = fr > 0 ? up[m] : (m > 0 ? up[m > 0 ? m - 1 : 0] : 0.f), next = fr < 15 ? dn[m] : (m < 3 ? dn[m < 3 ? m + 1 : 3] : 0.f);
;                         const float cv = b0 + w0 * prev + w1 * a[m] + w2 * next; out[m][e] = siluf_(cv) * acc[ai][1][m][n][e]; } }
; #pragma unroll
;                 for (int m = 0; m < 4; ++m) { const int r64 = 16 * m + fr, row = rowbase + r64;
;                     if (r64 != 0 && r64 != 63) { v2u w; w.x = pk2(out[m][0], out[m][1]); w.y = pk2(out[m][2], out[m][3]); *(GAS v2u*)(hg + (size_t)row * FFH + hc) = w; }
.LBB0_1561:
	s_or_b64 exec, exec, s[38:39]
	v_mov_b32_dpp v36, v30 row_ror:1 row_mask:0xf bank_mask:0xf
	v_mov_b32_dpp v68, v30 row_ror:15 row_mask:0xf bank_mask:0xf
	v_mov_b32_dpp v64, v22 row_ror:1 row_mask:0xf bank_mask:0xf
	v_mov_b32_dpp v66, v22 row_ror:15 row_mask:0xf bank_mask:0xf
	v_mov_b32_dpp v49, v18 row_ror:1 row_mask:0xf bank_mask:0xf
	v_mov_b32_dpp v65, v18 row_ror:15 row_mask:0xf bank_mask:0xf
	v_mov_b32_dpp v51, v6 row_ror:1 row_mask:0xf bank_mask:0xf
	v_mov_b32_dpp v41, v6 row_ror:15 row_mask:0xf bank_mask:0xf
	v_mov_b32_dpp v37, v31 row_ror:1 row_mask:0xf bank_mask:0xf
	v_mov_b32_dpp v69, v31 row_ror:15 row_mask:0xf bank_mask:0xf
	v_mov_b32_dpp v62, v23 row_ror:1 row_mask:0xf bank_mask:0xf
	v_mov_b32_dpp v67, v23 row_ror:15 row_mask:0xf bank_mask:0xf
	v_mov_b32_dpp v54, v19 row_ror:1 row_mask:0xf bank_mask:0xf
	v_mov_b32_dpp v63, v19 row_ror:15 row_mask:0xf bank_mask:0xf
	v_mov_b32_dpp v55, v7 row_ror:1 row_mask:0xf bank_mask:0xf
	v_mov_b32_dpp v53, v7 row_ror:15 row_mask:0xf bank_mask:0xf
	v_mov_b32_dpp v34, v32 row_ror:1 row_mask:0xf bank_mask:0xf
	v_mov_b32_dpp v72, v32 row_ror:15 row_mask:0xf bank_mask:0xf
	v_mov_b32_dpp v58, v24 row_ror:1 row_mask:0xf bank_mask:0xf
	v_mov_b32_dpp v60, v24 row_ror:15 row_mask:0xf bank_mask:0xf
	v_mov_b32_dpp v39, v20 row_ror:1 row_mask:0xf bank_mask:0xf
	v_mov_b32_dpp v59, v20 row_ror:15 row_mask:0xf bank_mask:0xf
	v_mov_b32_dpp v40, v8 row_ror:1 row_mask:0xf bank_mask:0xf
	v_mov_b32_dpp v38, v8 row_ror:15 row_mask:0xf bank_mask:0xf
	v_mov_b32_dpp v35, v33 row_ror:1 row_mask:0xf bank_mask:0xf
	v_mov_b32_dpp v73, v33 row_ror:15 row_mask:0xf bank_mask:0xf
	v_mov_b32_dpp v56, v25 row_ror:1 row_mask:0xf bank_mask:0xf
	v_mov_b32_dpp v61, v25 row_ror:15 row_mask:0xf bank_mask:0xf
	v_mov_b32_dpp v50, v21 row_ror:1 row_mask:0xf bank_mask:0xf
	v_mov_b32_dpp v57, v21 row_ror:15 row_mask:0xf bank_mask:0xf
	v_mov_b32_dpp v52, v9 row_ror:1 row_mask:0xf bank_mask:0xf
	v_mov_b32_dpp v48, v9 row_ror:15 row_mask:0xf bank_mask:0xf
	s_and_saveexec_b64 s[38:39], s[4:5]
	s_cbranch_execz .LBB0_1563
	v_fma_f32 v74, v106, v34, v112
	v_fma_f32 v75, v107, v35, v113
	v_cndmask_b32_e64 v73, v73, v61, s[6:7]
	v_fma_f32 v74, v32, v108, v74
	v_fma_f32 v75, v33, v109, v75
	v_cndmask_b32_e64 v72, v72, v60, s[6:7]
	v_fma_f32 v72, v72, v110, v74
	v_fma_f32 v73, v73, v111, v75
	v_cndmask_b32_e64 v69, v69, v67, s[6:7]
	v_mul_f32_e32 v74, 0xbfb8aa3b, v73
	v_exp_f32_e32 v74, v74
	v_mul_f32_e32 v75, 0xbfb8aa3b, v72
	v_exp_f32_e32 v76, v75
	v_cndmask_b32_e64 v68, v68, v66, s[6:7]
	v_add_f32_e32 v74, 1.0, v74
	v_rcp_f32_e32 v75, v74
	v_add_f32_e32 v74, 1.0, v76
	v_fma_f32 v76, v98, v36, v104
	v_fma_f32 v77, v99, v37, v105
	v_rcp_f32_e32 v74, v74
	v_fma_f32 v76, v30, v100, v76
	v_fma_f32 v77, v31, v101, v77
	v_mul_f32_e32 v72, v72, v74
	v_mul_f32_e32 v73, v73, v75
	v_fma_f32 v68, v68, v102, v76
	v_fma_f32 v69, v69, v103, v77
	v_mul_f32_e32 v72, v28, v72
	v_mul_f32_e32 v73, v29, v73
	v_mul_f32_e32 v76, 0xbfb8aa3b, v69
	v_exp_f32_e32 v76, v76
	v_mul_f32_e32 v77, 0xbfb8aa3b, v68
	v_exp_f32_e32 v78, v77
	v_add_f32_e32 v76, 1.0, v76
	v_rcp_f32_e32 v77, v76
	v_add_f32_e32 v76, 1.0, v78
	v_rcp_f32_e32 v76, v76
	s_nop 0
	v_mul_f32_e32 v68, v68, v76
	v_mul_f32_e32 v69, v69, v77
	s_nop 0
	v_mul_f32_e32 v68, v26, v68
	v_mul_f32_e32 v69, v27, v69
	s_nop 0
	v_cvt_pk_bf16_f32 v68, v68, v69
	v_cvt_pk_bf16_f32 v69, v72, v73
	v_mov_b64_e32 v[72:73], s[18:19]
	v_mad_i64_i32 v[72:73], s[42:43], v70, s65, v[72:73]
	v_lshl_add_u64 v[72:73], v[154:155], 1, v[72:73]
	global_store_dwordx2 v[72:73], v[68:69], off offset:8

; #define GAS __attribute__((address_space(1)))
; __device__ __forceinline__ unsigned pk2(float lo, float hi) { const f32x2cv v = {lo, hi}; return __builtin_bit_cast(unsigned, __builtin_convertvector(v, bf16x2cv)); }
;     __device__ __forceinline__ void operator()(const pg8::f32x4 (&acc)[2][2][4][2], const pg8::Unit& u, int wr, int wc, int fr, int fq) const {
;     ...
;                 const int hc = hc0 + 4 * n;
;                 float out[4][4];
; #pragma unroll
;                 for (int e = 0; e < 4; ++e) { const int c = 4 * n + e; const unsigned pw0 = (c & 1) ? wq[c >> 1].z : wq[c >> 1].x, pw1 = (c & 1) ? wq[c >> 1].w : wq[c >> 1].y;
;                     const float w0 = bflo(pw0), w1 = bfhi(pw0), w2 = bflo(pw1), b0 = bfhi(pw1);
;                     float a[4], up[4], dn[4];
; #pragma unroll
;                     for (int m = 0; m < 4; ++m) { a[m] = acc[ai][0][m][n][e];
;                         up[m] = __builtin_bit_cast(float, __builtin_amdgcn_mov_dpp(__builtin_bit_cast(int, a[m]), 0x121, 0xf, 0xf, false));
;                         dn[m] = __builtin_bit_cast(float, __builtin_amdgcn_mov_dpp(__builtin_bit_cast(int, a[m]), 0x12f, 0xf, 0xf, false)); }
; #pragma unroll
;                     for (int m = 0; m < 4; ++m) { const float prev = fr > 0 ? up[m] : (m > 0 ? up[m > 0 ? m - 1 : 0] : 0.f), next = fr < 15 ? dn[m] : (m < 3 ? dn[m < 3 ? m + 1 : 3] : 0.f);
;                         const float cv = b0 + w0 * prev + w1 * a[m] + w2 * next; out[m][e] = siluf_(cv) * acc[ai][1][m][n][e]; } }
; #pragma unroll
;                 for (int m = 0; m < 4; ++m) { const int r64 = 16 * m + fr, row = rowbase + r64;
;                     if (r64 != 0 && r64 != 63) { v2u w; w.x = pk2(out[m][0], out[m][1]); w.y = pk2(out[m][2], out[m][3]); *(GAS v2u*)(hg + (size_t)row * FFH + hc) = w; }
;                     if (r64 <= 1 || r64 >= 62) { const int slot = r64 <= 1 ? r64 : r64 - 60; const f32x4 ra = acc[ai][0][m][n];
;                         v2u w; w.x = pk2(ra[0], ra[1]); w.y = pk2(ra[2], ra[3]); *(GAS v2u*)(ab + (size_t)(g64 * 4 + slot) * FFH + hc) = w;
;                         if (r64 == 0 || r64 == 63) { const f32x4 rg = acc[ai][1][m][n]; v2u wg; wg.x = pk2(rg[0], rg[1]); wg.y = pk2(rg[2], rg[3]); *(GAS v2u*)(gb + (size_t)(g64 * 2 + (r64 == 63 ? 1 : 0)) * FFH + hc) = wg; } }
.LBB0_1566:
	s_or_b64 exec, exec, s[38:39]
	v_cndmask_b32_e64 v27, v62, v37, s[2:3]
	v_cndmask_b32_e64 v26, v64, v36, s[2:3]
	v_fma_f32 v26, v26, v98, v104
	v_fma_f32 v27, v27, v99, v105
	v_cndmask_b32_e64 v29, v67, v63, s[6:7]
	v_cndmask_b32_e64 v28, v66, v65, s[6:7]
	v_fma_f32 v22, v22, v100, v26
	v_fma_f32 v23, v23, v101, v27
	v_cndmask_b32_e64 v30, v63, v53, s[6:7]
	v_fma_f32 v22, v28, v102, v22
	v_fma_f32 v23, v29, v103, v23
	v_cndmask_b32_e64 v28, v49, v64, s[2:3]
	v_mul_f32_e32 v26, 0xbfb8aa3b, v22
	v_mul_f32_e32 v27, 0xbfb8aa3b, v23
	v_fma_f32 v28, v98, v28, v104
	v_exp_f32_e32 v26, v26
	v_exp_f32_e32 v27, v27
	v_cndmask_b32_e64 v29, v65, v41, s[6:7]
	v_fmac_f32_e32 v28, v18, v100
	v_fmac_f32_e32 v28, v102, v29
	v_mul_f32_e32 v18, 0xbfb8aa3b, v28
	v_exp_f32_e32 v29, v18
	v_cndmask_b32_e64 v18, v54, v62, s[2:3]
	v_add_f32_e32 v26, 1.0, v26
	v_add_f32_e32 v27, 1.0, v27
	v_fma_f32 v31, v99, v18, v105
	v_rcp_f32_e32 v26, v26
	v_rcp_f32_e32 v27, v27
	v_fmac_f32_e32 v31, v19, v101
	v_fmac_f32_e32 v31, v103, v30
	v_mul_f32_e32 v18, 0xbfb8aa3b, v31
	v_exp_f32_e32 v30, v18
	v_mul_f32_e32 v18, v22, v26
	v_mul_f32_e32 v19, v23, v27
	v_add_f32_e32 v22, 1.0, v29
	v_rcp_f32_e32 v22, v22
	v_add_f32_e32 v23, 1.0, v30
	v_rcp_f32_e32 v23, v23
	v_mul_f32_e32 v14, v14, v18
	v_mul_f32_e32 v15, v15, v19
	v_mul_f32_e32 v18, v28, v22
	v_mul_f32_e32 v26, v10, v18
	v_cndmask_b32_e64 v19, v56, v35, s[2:3]
	v_cndmask_b32_e64 v18, v58, v34, s[2:3]
	v_fma_f32 v18, v18, v106, v112
	v_fma_f32 v19, v19, v107, v113
	v_mul_f32_e32 v10, v31, v23
	v_cndmask_b32_e64 v23, v61, v57, s[6:7]
	v_cndmask_b32_e64 v22, v60, v59, s[6:7]
	v_fma_f32 v18, v24, v108, v18
	v_fma_f32 v19, v25, v109, v19
	v_mul_f32_e32 v24, v11, v10
	v_fma_f32 v18, v22, v110, v18
	v_fma_f32 v19, v23, v111, v19
	v_cndmask_b32_e64 v25, v57, v48, s[6:7]
	v_mul_f32_e32 v22, 0xbfb8aa3b, v18
	v_exp_f32_e32 v22, v22
	v_mul_f32_e32 v23, 0xbfb8aa3b, v19
	v_exp_f32_e32 v23, v23
	v_add_f32_e32 v10, 1.0, v22
	v_cndmask_b32_e64 v22, v39, v58, s[2:3]
	v_fma_f32 v22, v106, v22, v112
	v_add_f32_e32 v11, 1.0, v23
	v_cndmask_b32_e64 v23, v59, v38, s[6:7]
	v_fmac_f32_e32 v22, v20, v108
	v_fmac_f32_e32 v22, v110, v23
	v_cndmask_b32_e64 v23, v50, v56, s[2:3]
	v_fma_f32 v23, v107, v23, v113
	v_fmac_f32_e32 v23, v21, v109
	v_mul_f32_e32 v20, 0xbfb8aa3b, v22
	v_fmac_f32_e32 v23, v111, v25
	v_rcp_f32_e32 v10, v10
	v_rcp_f32_e32 v11, v11
	v_exp_f32_e32 v20, v20
	v_mul_f32_e32 v21, 0xbfb8aa3b, v23
	v_exp_f32_e32 v21, v21
	v_mul_f32_e32 v10, v18, v10
	v_mul_f32_e32 v11, v19, v11
	v_add_f32_e32 v18, 1.0, v20
	v_rcp_f32_e32 v18, v18
	v_add_f32_e32 v19, 1.0, v21
	v_rcp_f32_e32 v19, v19
	v_mul_f32_e32 v10, v16, v10
	v_mul_f32_e32 v11, v17, v11
	v_mul_f32_e32 v16, v22, v18
	v_mul_f32_e32 v16, v12, v16
	v_mul_f32_e32 v12, v23, v19
	v_mul_f32_e32 v17, v13, v12
	v_cvt_pk_bf16_f32 v12, v14, v15
	v_cvt_pk_bf16_f32 v13, v10, v11
	v_cvt_pk_bf16_f32 v10, v26, v24
	v_cvt_pk_bf16_f32 v11, v16, v17
	global_store_dwordx2 v[42:43], v[12:13], off offset:8
	global_store_dwordx2 v[44:45], v[10:11], off offset:8
	s_and_saveexec_b64 s[38:39], s[8:9]
	s_cbranch_execz .LBB0_1568
	v_cndmask_b32_e64 v10, v51, v49, s[2:3]
	v_cndmask_b32_e64 v11, v55, v54, s[2:3]
	v_cndmask_b32_e64 v14, v40, v39, s[2:3]
	v_cndmask_b32_e64 v15, v52, v50, s[2:3]
	v_fma_f32 v10, v10, v98, v104
	v_fma_f32 v11, v11, v99, v105
	v_fma_f32 v14, v14, v106, v112
	v_fma_f32 v15, v15, v107, v113
	v_cndmask_b32_e64 v12, v41, 0, s[6:7]
	v_cndmask_b32_e64 v13, v53, 0, s[6:7]
	v_fma_f32 v10, v6, v100, v10
	v_fma_f32 v11, v7, v101, v11
	v_cndmask_b32_e64 v16, v38, 0, s[6:7]
	v_cndmask_b32_e64 v17, v48, 0, s[6:7]
	v_fma_f32 v14, v8, v108, v14
	v_fma_f32 v15, v9, v109, v15
	v_fma_f32 v10, v12, v102, v10
	v_fma_f32 v11, v13, v103, v11
	v_fma_f32 v14, v16, v110, v14
	v_fma_f32 v15, v17, v111, v15
	v_mul_f32_e32 v12, 0xbfb8aa3b, v10
	v_mul_f32_e32 v13, 0xbfb8aa3b, v11
	v_mul_f32_e32 v16, 0xbfb8aa3b, v14
	v_mul_f32_e32 v17, 0xbfb8aa3b, v15
	v_exp_f32_e32 v12, v12
	v_exp_f32_e32 v13, v13
	v_exp_f32_e32 v16, v16
	v_exp_f32_e32 v17, v17
	v_add_f32_e32 v12, 1.0, v12
	v_add_f32_e32 v13, 1.0, v13
	v_add_f32_e32 v16, 1.0, v16
	v_add_f32_e32 v17, 1.0, v17
	v_rcp_f32_e32 v12, v12
	v_rcp_f32_e32 v13, v13
	v_rcp_f32_e32 v16, v16
	v_rcp_f32_e32 v17, v17
	v_mul_f32_e32 v10, v10, v12
	v_mul_f32_e32 v11, v11, v13
	s_nop 0
	v_mul_f32_e32 v10, v2, v10
	v_mul_f32_e32 v11, v3, v11
	v_mul_f32_e32 v12, v14, v16
	v_mul_f32_e32 v13, v15, v17
	v_cvt_pk_bf16_f32 v10, v10, v11
	v_mul_f32_e32 v12, v4, v12
	v_mul_f32_e32 v13, v5, v13
	s_nop 0
	v_cvt_pk_bf16_f32 v11, v12, v13
	v_mov_b64_e32 v[12:13], s[18:19]
	v_mad_i64_i32 v[12:13], s[42:43], v46, s65, v[12:13]
	v_lshl_add_u64 v[12:13], v[154:155], 1, v[12:13]
	global_store_dwordx2 v[12:13], v[10:11], off offset:8
